# phase-0 boundary uses the XCD hierarchical barrier instead of cooperative-groups grid sync
# speedup vs baseline: 1.0072x; 1.0072x over previous
.LBB0_856:
	v_readlane_b32 s62, v255, 8
	v_readlane_b32 s63, v255, 9
	s_add_i32 s3, s62, 1
	s_cmp_ge_i32 s3, s63
	s_mov_b64 s[0:1], -1
	s_cbranch_scc1 .LBB0_10
	s_nop 0
	s_waitcnt vmcnt(0)
	s_waitcnt vmcnt(0) lgkmcnt(0)
	s_barrier
	s_mov_b64 s[0:1], exec
	v_readlane_b32 s28, v250, 3
	v_readlane_b32 s29, v250, 4
	s_and_b64 s[28:29], s[0:1], s[28:29]
	s_mov_b64 exec, s[28:29]
	s_cbranch_execz .LBB0_910
	v_readlane_b32 s28, v254, 40
	s_waitcnt vmcnt(0) expcnt(0) lgkmcnt(0)
	s_nop 0
	v_mov_b32_e32 v0, s28
	ds_read_b32 v3, v0
	v_readlane_b32 s28, v254, 41
	s_waitcnt lgkmcnt(0)
	v_cmp_ne_u32_e32 vcc, 0, v3
	v_mov_b32_e32 v0, s28
	ds_read_b32 v2, v0
	s_cbranch_vccnz .LBB0_874
	s_mov_b32 s33, 1
	s_branch .LBB0_862
